# merge: next sub-GEMM's setup and first four K slices issued before the current sub-GEMM's gate epilogue (overlaps LDS-DMA fill with gate loads)
# baseline (speedup 1.0000x reference)
.LBB0_1183:
	s_add_i32 s1, s1, 1
	s_cmp_eq_u32 s1, 4
	s_cbranch_scc1 .Lmg_epi
	s_cmp_lt_i32 s1, 1
	s_cbranch_scc1 .Lmgc_1192
	s_cmp_lt_i32 s1, 2
	s_mov_b64 s[78:79], -1
	s_cbranch_scc1 .Lmgc_1190
	s_cmp_lg_u32 s1, 2
	s_mov_b64 s[26:27], -1
	s_cbranch_scc0 .Lmgc_1188
	s_mov_b64 s[26:27], 0

.Lmgc_1193:
	v_mov_b32_e32 v208, v166
	s_add_u32 s66, s92, s26
	s_addc_u32 s78, s93, s27
	v_lshlrev_b32_e32 v210, 4, v208
	v_and_b32_e32 v211, 32, v208
	s_lshl_b32 vcc_lo, s25, 1
	v_ashrrev_i32_e32 v209, 6, v208
	v_bitop3_b32 v210, v210, v211, 48 bitop3:0x6c
	s_add_u32 s25, s66, vcc_lo
	v_lshrrev_b32_e32 v208, 2, v208
	v_lshrrev_b32_e32 v216, 1, v210
	v_lshlrev_b32_e32 v210, 4, v209
	s_addc_u32 s66, s78, 0
	s_mul_hi_i32 s79, s67, s24
	s_mul_i32 s78, s67, s24
	v_and_or_b32 v210, v208, 15, v210
	v_mov_b32_e32 v220, v166
	s_lshl_b64 s[78:79], s[78:79], 1
	v_mul_lo_u32 v217, v210, s61
	v_lshlrev_b32_e32 v165, 10, v209
	v_and_b32_e32 v211, 15, v220
	v_lshlrev_b32_e32 v213, 2, v220
	s_add_u32 s78, s25, s78
	v_or_b32_e32 v64, v217, v216
	v_mul_lo_u32 v218, v210, s67
	v_add_u32_e32 v210, 0x80, v210
	v_and_b32_e32 v212, 48, v220
	v_lshlrev_b32_e32 v211, 6, v211
	v_and_b32_e32 v213, 32, v213
	v_readfirstlane_b32 s61, v165
	v_add_u32_e32 v214, 0x2000, v165
	s_addc_u32 s79, s66, s79
	v_or_b32_e32 v208, v218, v216
	v_mul_lo_u32 v219, v210, s67
	v_bitop3_b32 v164, v211, v213, v212 bitop3:0x36
	v_lshl_add_u64 v[212:213], v[64:65], 1, s[38:39]
	v_mov_b32_e32 v209, v65
	s_mov_b32 m0, s61
	v_readfirstlane_b32 s61, v214
	v_add_u32_e32 v214, 0x4000, v165
	v_or_b32_e32 v210, v219, v216
	s_barrier
	v_mov_b32_e32 v211, v65
	global_load_lds_dwordx4 v[212:213], off
	v_lshl_add_u64 v[208:209], v[208:209], 1, s[78:79]
	s_mov_b32 m0, s61
	v_readfirstlane_b32 s61, v214
	v_add_u32_e32 v221, 0x6000, v165
	global_load_lds_dwordx4 v[208:209], off
	v_lshl_add_u64 v[210:211], v[210:211], 1, s[78:79]
	s_mov_b32 m0, s61
	v_readfirstlane_b32 s61, v221
	v_add_u32_e32 v221, 0x8000, v165
	global_load_lds_dwordx4 v[210:211], off
	v_lshl_add_u64 v[214:215], v[212:213], 0, 64
	s_mov_b32 m0, s61
	v_readfirstlane_b32 s61, v221
	v_add_u32_e32 v221, 0xa000, v165
	global_load_lds_dwordx4 v[214:215], off
	v_lshl_add_u64 v[214:215], v[208:209], 0, 64
	s_mov_b32 m0, s61
	v_readfirstlane_b32 s61, v221
	v_add_u32_e32 v221, 0xc000, v165
	global_load_lds_dwordx4 v[214:215], off
	v_lshl_add_u64 v[214:215], v[210:211], 0, 64
	s_mov_b32 m0, s61
	v_readfirstlane_b32 s61, v221
	v_add_u32_e32 v221, 0xe000, v165
	global_load_lds_dwordx4 v[214:215], off
	v_lshl_add_u64 v[214:215], v[212:213], 0, s[34:35]
	s_mov_b32 m0, s61
	v_readfirstlane_b32 s61, v221
	v_add_u32_e32 v221, 0x10000, v165
	global_load_lds_dwordx4 v[214:215], off
	v_lshl_add_u64 v[214:215], v[208:209], 0, s[34:35]
	s_mov_b32 m0, s61
	v_readfirstlane_b32 s61, v221
	global_load_lds_dwordx4 v[214:215], off
	v_lshl_add_u64 v[214:215], v[210:211], 0, s[34:35]
	s_mov_b32 m0, s61
	v_lshl_add_u64 v[212:213], v[212:213], 0, s[82:83]
	global_load_lds_dwordx4 v[214:215], off
	v_add_u32_e32 v214, 0x12000, v165
	v_lshl_add_u64 v[208:209], v[208:209], 0, s[82:83]
	v_readfirstlane_b32 s61, v214
	s_mov_b32 m0, s61
	v_add_u32_e32 v64, v216, v217
	global_load_lds_dwordx4 v[212:213], off
	v_add_u32_e32 v212, 0x14000, v165
	s_mov_b32 s25, 4
	v_readfirstlane_b32 s61, v212
	s_mov_b32 m0, s61
	s_nop 0
	global_load_lds_dwordx4 v[208:209], off
	v_lshl_add_u64 v[208:209], v[210:211], 0, s[82:83]
	v_add_u32_e32 v210, 0x16000, v165
	s_nop 0
	v_readfirstlane_b32 s61, v210
	s_mov_b32 m0, s61
	s_lshr_b32 s61, s67, 5
	global_load_lds_dwordx4 v[208:209], off
	v_lshlrev_b32_e32 v208, 4, v220
	v_and_b32_e32 v197, 0xfffff000, v208
	v_lshlrev_b32_e32 v208, 6, v220
	v_and_b32_e32 v198, 0x3000, v208
	v_lshl_add_u64 v[208:209], v[64:65], 1, s[38:39]
	s_mov_b64 s[38:39], 0x100
	v_lshl_add_u64 v[158:159], v[208:209], 0, s[38:39]
	s_mul_i32 s38, s65, s67
	s_mul_hi_u32 s39, s64, s67
	s_add_i32 s66, s61, -1
	s_add_i32 s39, s39, s38
	s_mul_i32 s38, s64, s67
	s_add_u32 s26, s26, s38
	s_addc_u32 s27, s27, s39
	s_add_u32 s26, s26, vcc_lo
	s_addc_u32 s27, s27, 0
	s_add_u32 s26, s62, s26
	v_add_u32_e32 v64, v216, v218
	s_addc_u32 s27, s63, s27
	v_lshl_add_u64 v[160:161], v[64:65], 1, s[26:27]
	v_add_u32_e32 v64, v216, v219
	v_lshl_add_u64 v[162:163], v[64:65], 1, s[26:27]
	s_mov_b32 s67, 0
	s_mov_b64 s[26:27], 0
.Lmg_epi:
	s_mov_b32 s38, s0
	s_mul_hi_i32 s96, s38, 0x230000
	s_mul_i32 s38, s38, 0x230000
	s_add_u32 s38, s92, s38
	s_addc_u32 s96, s93, s96
	s_lshl_b32 s97, s1, 11
	s_sub_u32 s97, s97, 0x800
	s_add_u32 s38, s38, s97
	s_addc_u32 s96, s96, 0
	s_add_u32 s38, s38, s64
	v_mov_b32_e32 v64, v166
	s_addc_u32 s97, s96, s65
	s_add_u32 s96, s38, 0x23606f00
	v_and_b32_e32 v66, 0xc0, v64
	v_and_b32_e32 v67, 15, v64
	v_lshrrev_b32_e32 v64, 2, v64
	s_mov_b32 s38, 0xffffc0
	v_and_or_b32 v67, v64, s38, v67
	v_and_b32_e32 v64, 12, v64
	v_mul_u32_u24_e32 v67, 0x2300, v67
	s_addc_u32 s97, s97, 0
	v_or3_b32 v64, v64, v66, v67
	v_lshl_add_u64 v[246:247], v[64:65], 1, s[96:97]
	v_add_u32_e32 v248, 0x23000, v64
	v_mov_b32_e32 v249, 0
	v_lshl_add_u64 v[248:249], v[248:249], 1, s[96:97]
	v_add_u32_e32 v250, 0x46000, v64
	v_mov_b32_e32 v251, 0
	v_lshl_add_u64 v[250:251], v[250:251], 1, s[96:97]
	v_add_u32_e32 v252, 0x69000, v64
	v_mov_b32_e32 v253, 0
	v_lshl_add_u64 v[252:253], v[252:253], 1, s[96:97]
	global_load_dwordx2 v[66:67], v[246:247], off
	global_load_dwordx2 v[68:69], v[246:247], off offset:32
	global_load_dwordx2 v[70:71], v[246:247], off offset:64
	global_load_dwordx2 v[72:73], v[246:247], off offset:96
	global_load_dwordx2 v[74:75], v[248:249], off
	global_load_dwordx2 v[76:77], v[248:249], off offset:32
	global_load_dwordx2 v[78:79], v[248:249], off offset:64
	global_load_dwordx2 v[80:81], v[248:249], off offset:96
	global_load_dwordx2 v[82:83], v[250:251], off
	global_load_dwordx2 v[84:85], v[250:251], off offset:32
	global_load_dwordx2 v[86:87], v[250:251], off offset:64
	global_load_dwordx2 v[88:89], v[250:251], off offset:96
	global_load_dwordx2 v[200:201], v[252:253], off
	global_load_dwordx2 v[202:203], v[252:253], off offset:32
	global_load_dwordx2 v[204:205], v[252:253], off offset:64
	global_load_dwordx2 v[206:207], v[252:253], off offset:96
	s_waitcnt vmcnt(15)
	v_lshlrev_b32_e32 v254, 16, v66
	v_and_b32_e32 v255, 0xffff0000, v66
	v_pk_fma_f32 v[144:145], v[60:61], v[254:255], v[144:145]
	v_lshlrev_b32_e32 v66, 16, v67
	v_and_b32_e32 v67, 0xffff0000, v67
	v_pk_fma_f32 v[152:153], v[62:63], v[66:67], v[152:153]
	s_waitcnt vmcnt(14)
	v_lshlrev_b32_e32 v254, 16, v68
	v_and_b32_e32 v255, 0xffff0000, v68
	v_pk_fma_f32 v[146:147], v[56:57], v[254:255], v[146:147]
	v_lshlrev_b32_e32 v68, 16, v69
	v_and_b32_e32 v69, 0xffff0000, v69
	v_pk_fma_f32 v[150:151], v[58:59], v[68:69], v[150:151]
	s_waitcnt vmcnt(13)
	v_lshlrev_b32_e32 v254, 16, v70
	v_and_b32_e32 v255, 0xffff0000, v70
	v_pk_fma_f32 v[140:141], v[52:53], v[254:255], v[140:141]
	v_lshlrev_b32_e32 v70, 16, v71
	v_and_b32_e32 v71, 0xffff0000, v71
	v_pk_fma_f32 v[148:149], v[54:55], v[70:71], v[148:149]
	s_waitcnt vmcnt(12)
	v_lshlrev_b32_e32 v254, 16, v72
	v_and_b32_e32 v255, 0xffff0000, v72
	v_pk_fma_f32 v[138:139], v[48:49], v[254:255], v[138:139]
	v_lshlrev_b32_e32 v72, 16, v73
	v_and_b32_e32 v73, 0xffff0000, v73
	v_pk_fma_f32 v[142:143], v[50:51], v[72:73], v[142:143]
	s_waitcnt vmcnt(11)
	v_lshlrev_b32_e32 v254, 16, v74
	v_and_b32_e32 v255, 0xffff0000, v74
	v_pk_fma_f32 v[134:135], v[44:45], v[254:255], v[134:135]
	v_lshlrev_b32_e32 v74, 16, v75
	v_and_b32_e32 v75, 0xffff0000, v75
	v_pk_fma_f32 v[136:137], v[46:47], v[74:75], v[136:137]
	s_waitcnt vmcnt(10)
	v_lshlrev_b32_e32 v254, 16, v76
	v_and_b32_e32 v255, 0xffff0000, v76
	v_pk_fma_f32 v[130:131], v[40:41], v[254:255], v[130:131]
	v_lshlrev_b32_e32 v76, 16, v77
	v_and_b32_e32 v77, 0xffff0000, v77
	v_pk_fma_f32 v[132:133], v[42:43], v[76:77], v[132:133]
	s_waitcnt vmcnt(9)
	v_lshlrev_b32_e32 v254, 16, v78
	v_and_b32_e32 v255, 0xffff0000, v78
	v_pk_fma_f32 v[126:127], v[36:37], v[254:255], v[126:127]
	v_lshlrev_b32_e32 v78, 16, v79
	v_and_b32_e32 v79, 0xffff0000, v79
	v_pk_fma_f32 v[128:129], v[38:39], v[78:79], v[128:129]
	s_waitcnt vmcnt(8)
	v_lshlrev_b32_e32 v254, 16, v80
	v_and_b32_e32 v255, 0xffff0000, v80
	v_pk_fma_f32 v[122:123], v[32:33], v[254:255], v[122:123]
	v_lshlrev_b32_e32 v80, 16, v81
	v_and_b32_e32 v81, 0xffff0000, v81
	v_pk_fma_f32 v[124:125], v[34:35], v[80:81], v[124:125]
	s_waitcnt vmcnt(7)
	v_lshlrev_b32_e32 v254, 16, v82
	v_and_b32_e32 v255, 0xffff0000, v82
	v_pk_fma_f32 v[118:119], v[28:29], v[254:255], v[118:119]
	v_lshlrev_b32_e32 v82, 16, v83
	v_and_b32_e32 v83, 0xffff0000, v83
	v_pk_fma_f32 v[120:121], v[30:31], v[82:83], v[120:121]
	s_waitcnt vmcnt(6)
	v_lshlrev_b32_e32 v254, 16, v84
	v_and_b32_e32 v255, 0xffff0000, v84
	v_pk_fma_f32 v[114:115], v[24:25], v[254:255], v[114:115]
	v_lshlrev_b32_e32 v84, 16, v85
	v_and_b32_e32 v85, 0xffff0000, v85
	v_pk_fma_f32 v[116:117], v[26:27], v[84:85], v[116:117]
	s_waitcnt vmcnt(5)
	v_lshlrev_b32_e32 v254, 16, v86
	v_and_b32_e32 v255, 0xffff0000, v86
	v_pk_fma_f32 v[110:111], v[20:21], v[254:255], v[110:111]
	v_lshlrev_b32_e32 v86, 16, v87
	v_and_b32_e32 v87, 0xffff0000, v87
	v_pk_fma_f32 v[112:113], v[22:23], v[86:87], v[112:113]
	s_waitcnt vmcnt(4)
	v_lshlrev_b32_e32 v254, 16, v88
	v_and_b32_e32 v255, 0xffff0000, v88
	v_pk_fma_f32 v[106:107], v[16:17], v[254:255], v[106:107]
	v_lshlrev_b32_e32 v88, 16, v89
	v_and_b32_e32 v89, 0xffff0000, v89
	v_pk_fma_f32 v[108:109], v[18:19], v[88:89], v[108:109]
	s_waitcnt vmcnt(3)
	v_lshlrev_b32_e32 v254, 16, v200
	v_and_b32_e32 v255, 0xffff0000, v200
	v_pk_fma_f32 v[102:103], v[12:13], v[254:255], v[102:103]
	v_lshlrev_b32_e32 v200, 16, v201
	v_and_b32_e32 v201, 0xffff0000, v201
	v_pk_fma_f32 v[104:105], v[14:15], v[200:201], v[104:105]
	s_waitcnt vmcnt(2)
	v_lshlrev_b32_e32 v254, 16, v202
	v_and_b32_e32 v255, 0xffff0000, v202
	v_pk_fma_f32 v[98:99], v[8:9], v[254:255], v[98:99]
	v_lshlrev_b32_e32 v202, 16, v203
	v_and_b32_e32 v203, 0xffff0000, v203
	v_pk_fma_f32 v[100:101], v[10:11], v[202:203], v[100:101]
	s_waitcnt vmcnt(1)
	v_lshlrev_b32_e32 v254, 16, v204
	v_and_b32_e32 v255, 0xffff0000, v204
	v_pk_fma_f32 v[94:95], v[4:5], v[254:255], v[94:95]
	v_lshlrev_b32_e32 v204, 16, v205
	v_and_b32_e32 v205, 0xffff0000, v205
	v_pk_fma_f32 v[96:97], v[6:7], v[204:205], v[96:97]
	s_waitcnt vmcnt(0)
	v_lshlrev_b32_e32 v254, 16, v206
	v_and_b32_e32 v255, 0xffff0000, v206
	v_pk_fma_f32 v[90:91], v[0:1], v[254:255], v[90:91]
	v_lshlrev_b32_e32 v206, 16, v207
	v_and_b32_e32 v207, 0xffff0000, v207
	v_pk_fma_f32 v[92:93], v[2:3], v[206:207], v[92:93]
	s_cmp_eq_u32 s1, 4
	s_cbranch_scc1 .LBB0_1171
	s_branch .Lmg_zero
.Lmgc_1211:
	s_mov_b64 s[26:27], 0x2b00000
	s_movk_i32 s61, 0x100
	s_mov_b64 s[38:39], s[80:81]
	s_movk_i32 s67, 0x100
	s_mov_b32 s25, s21
	s_cbranch_execz .Lmgc_1191
	s_branch .Lmgc_1193
.LBB0_1184:
	s_cmp_lt_i32 s1, 1
	s_cbranch_scc1 .LBB0_1192
	s_cmp_lt_i32 s1, 2
	s_mov_b64 s[78:79], -1
	s_cbranch_scc1 .LBB0_1190
	s_cmp_lg_u32 s1, 2
	s_mov_b64 s[26:27], -1
	s_cbranch_scc0 .LBB0_1188
	s_mov_b64 s[26:27], 0

.LBB0_1193:
	v_mov_b32_e32 v0, v166
	s_add_u32 s66, s92, s26
	s_addc_u32 s78, s93, s27
	v_lshlrev_b32_e32 v2, 4, v0
	v_and_b32_e32 v3, 32, v0
	s_lshl_b32 vcc_lo, s25, 1
	v_ashrrev_i32_e32 v1, 6, v0
	v_bitop3_b32 v2, v2, v3, 48 bitop3:0x6c
	s_add_u32 s25, s66, vcc_lo
	v_lshrrev_b32_e32 v0, 2, v0
	v_lshrrev_b32_e32 v8, 1, v2
	v_lshlrev_b32_e32 v2, 4, v1
	s_addc_u32 s66, s78, 0
	s_mul_hi_i32 s79, s67, s24
	s_mul_i32 s78, s67, s24
	v_and_or_b32 v2, v0, 15, v2
	v_mov_b32_e32 v12, v166
	s_lshl_b64 s[78:79], s[78:79], 1
	v_mul_lo_u32 v9, v2, s61
	v_lshlrev_b32_e32 v165, 10, v1
	v_and_b32_e32 v3, 15, v12
	v_lshlrev_b32_e32 v5, 2, v12
	s_add_u32 s78, s25, s78
	v_or_b32_e32 v64, v9, v8
	v_mul_lo_u32 v10, v2, s67
	v_add_u32_e32 v2, 0x80, v2
	v_and_b32_e32 v4, 48, v12
	v_lshlrev_b32_e32 v3, 6, v3
	v_and_b32_e32 v5, 32, v5
	v_readfirstlane_b32 s61, v165
	v_add_u32_e32 v6, 0x2000, v165
	s_addc_u32 s79, s66, s79
	v_or_b32_e32 v0, v10, v8
	v_mul_lo_u32 v11, v2, s67
	v_bitop3_b32 v164, v3, v5, v4 bitop3:0x36
	v_lshl_add_u64 v[4:5], v[64:65], 1, s[38:39]
	v_mov_b32_e32 v1, v65
	s_mov_b32 m0, s61
	v_readfirstlane_b32 s61, v6
	v_add_u32_e32 v6, 0x4000, v165
	v_or_b32_e32 v2, v11, v8
	s_barrier
	v_mov_b32_e32 v3, v65
	global_load_lds_dwordx4 v[4:5], off
	v_lshl_add_u64 v[0:1], v[0:1], 1, s[78:79]
	s_mov_b32 m0, s61
	v_readfirstlane_b32 s61, v6
	v_add_u32_e32 v13, 0x6000, v165
	global_load_lds_dwordx4 v[0:1], off
	v_lshl_add_u64 v[2:3], v[2:3], 1, s[78:79]
	s_mov_b32 m0, s61
	v_readfirstlane_b32 s61, v13
	v_add_u32_e32 v13, 0x8000, v165
	global_load_lds_dwordx4 v[2:3], off
	v_lshl_add_u64 v[6:7], v[4:5], 0, 64
	s_mov_b32 m0, s61
	v_readfirstlane_b32 s61, v13
	v_add_u32_e32 v13, 0xa000, v165
	global_load_lds_dwordx4 v[6:7], off
	v_lshl_add_u64 v[6:7], v[0:1], 0, 64
	s_mov_b32 m0, s61
	v_readfirstlane_b32 s61, v13
	v_add_u32_e32 v13, 0xc000, v165
	global_load_lds_dwordx4 v[6:7], off
	v_lshl_add_u64 v[6:7], v[2:3], 0, 64
	s_mov_b32 m0, s61
	v_readfirstlane_b32 s61, v13
	v_add_u32_e32 v13, 0xe000, v165
	global_load_lds_dwordx4 v[6:7], off
	v_lshl_add_u64 v[6:7], v[4:5], 0, s[34:35]
	s_mov_b32 m0, s61
	v_readfirstlane_b32 s61, v13
	v_add_u32_e32 v13, 0x10000, v165
	global_load_lds_dwordx4 v[6:7], off
	v_lshl_add_u64 v[6:7], v[0:1], 0, s[34:35]
	s_mov_b32 m0, s61
	v_readfirstlane_b32 s61, v13
	global_load_lds_dwordx4 v[6:7], off
	v_lshl_add_u64 v[6:7], v[2:3], 0, s[34:35]
	s_mov_b32 m0, s61
	v_lshl_add_u64 v[4:5], v[4:5], 0, s[82:83]
	global_load_lds_dwordx4 v[6:7], off
	v_add_u32_e32 v6, 0x12000, v165
	v_lshl_add_u64 v[0:1], v[0:1], 0, s[82:83]
	v_readfirstlane_b32 s61, v6
	s_mov_b32 m0, s61
	v_add_u32_e32 v64, v8, v9
	global_load_lds_dwordx4 v[4:5], off
	v_add_u32_e32 v4, 0x14000, v165
	s_mov_b32 s25, 4
	v_readfirstlane_b32 s61, v4
	s_mov_b32 m0, s61
	s_nop 0
	global_load_lds_dwordx4 v[0:1], off
	v_lshl_add_u64 v[0:1], v[2:3], 0, s[82:83]
	v_add_u32_e32 v2, 0x16000, v165
	s_nop 0
	v_readfirstlane_b32 s61, v2
	s_mov_b32 m0, s61
	s_lshr_b32 s61, s67, 5
	global_load_lds_dwordx4 v[0:1], off
	v_lshlrev_b32_e32 v0, 4, v12
	v_and_b32_e32 v197, 0xfffff000, v0
	v_lshlrev_b32_e32 v0, 6, v12
	v_and_b32_e32 v198, 0x3000, v0
	v_lshl_add_u64 v[0:1], v[64:65], 1, s[38:39]
	s_mov_b64 s[38:39], 0x100
	v_lshl_add_u64 v[158:159], v[0:1], 0, s[38:39]
	s_mul_i32 s38, s65, s67
	s_mul_hi_u32 s39, s64, s67
	s_add_i32 s66, s61, -1
	s_add_i32 s39, s39, s38
	s_mul_i32 s38, s64, s67
	s_add_u32 s26, s26, s38
	s_addc_u32 s27, s27, s39
	s_add_u32 s26, s26, vcc_lo
	s_addc_u32 s27, s27, 0
	s_add_u32 s26, s62, s26
	v_add_u32_e32 v64, v8, v10
	s_addc_u32 s27, s63, s27
	v_lshl_add_u64 v[160:161], v[64:65], 1, s[26:27]
	v_add_u32_e32 v64, v8, v11
	v_lshl_add_u64 v[162:163], v[64:65], 1, s[26:27]
	s_mov_b32 s67, 0
	s_mov_b64 s[26:27], 0
.Lmg_zero:
	v_mov_b32_e32 v0, 0
	v_mov_b32_e32 v1, v0
	v_mov_b32_e32 v2, v0
	v_mov_b32_e32 v3, v0
	v_mov_b32_e32 v4, v0
	v_mov_b32_e32 v5, v0
	v_mov_b32_e32 v6, v0
	v_mov_b32_e32 v7, v0
	v_mov_b32_e32 v8, v0
	v_mov_b32_e32 v9, v0
	v_mov_b32_e32 v10, v0
	v_mov_b32_e32 v11, v0
	v_mov_b32_e32 v12, v0
	v_mov_b32_e32 v13, v0
	v_mov_b32_e32 v14, v0
	v_mov_b32_e32 v15, v0
	v_mov_b32_e32 v16, v0
	v_mov_b32_e32 v17, v0
	v_mov_b32_e32 v18, v0
	v_mov_b32_e32 v19, v0
	v_mov_b32_e32 v20, v0
	v_mov_b32_e32 v21, v0
	v_mov_b32_e32 v22, v0
	v_mov_b32_e32 v23, v0
	v_mov_b32_e32 v24, v0
	v_mov_b32_e32 v25, v0
	v_mov_b32_e32 v26, v0
	v_mov_b32_e32 v27, v0
	v_mov_b32_e32 v28, v0
	v_mov_b32_e32 v29, v0
	v_mov_b32_e32 v30, v0
	v_mov_b32_e32 v31, v0
	v_mov_b32_e32 v32, v0
	v_mov_b32_e32 v33, v0
	v_mov_b32_e32 v34, v0
	v_mov_b32_e32 v35, v0
	v_mov_b32_e32 v36, v0
	v_mov_b32_e32 v37, v0
	v_mov_b32_e32 v38, v0
	v_mov_b32_e32 v39, v0
	v_mov_b32_e32 v40, v0
	v_mov_b32_e32 v41, v0
	v_mov_b32_e32 v42, v0
	v_mov_b32_e32 v43, v0
	v_mov_b32_e32 v44, v0
	v_mov_b32_e32 v45, v0
	v_mov_b32_e32 v46, v0
	v_mov_b32_e32 v47, v0
	v_mov_b32_e32 v48, v0
	v_mov_b32_e32 v49, v0
	v_mov_b32_e32 v50, v0
	v_mov_b32_e32 v51, v0
	v_mov_b32_e32 v52, v0
	v_mov_b32_e32 v53, v0
	v_mov_b32_e32 v54, v0
	v_mov_b32_e32 v55, v0
	v_mov_b32_e32 v56, v0
	v_mov_b32_e32 v57, v0
	v_mov_b32_e32 v58, v0
	v_mov_b32_e32 v59, v0
	v_mov_b32_e32 v60, v0
	v_mov_b32_e32 v61, v0
	v_mov_b32_e32 v62, v0
	v_mov_b32_e32 v63, v0
	s_branch .LBB0_1195
